# speedup vs baseline: 1.0280x; 1.0068x over previous
; __device__ __forceinline__ float bf2f(u16 h) { return __uint_as_float(((unsigned)h) << 16); }
; __device__ __forceinline__ float siluf_(float v) { return v * __builtin_amdgcn_rcpf(1.f + __expf(-v)); }
; template <int DUMMY>
; __device__ void ssd_item(const Params& p, int item) {
;     ...
;       for (int i = 0; i < 2; ++i) {
;         int idx = tid + i * NT;
;         *(i32x4*)(Bs + (idx >> 4) * 136 + (idx & 15) * 8) = rBs[i];
;         *(i32x4*)(Cs + (idx >> 4) * 136 + (idx & 15) * 8) = rCs[i];
;         int c8 = idx >> 6, ll = idx & 63;
; #pragma unroll
;         for (int e = 0; e < 4; ++e) {
;           unsigned u = (unsigned)rBT[i][e];
;           BTs[(c8 * 8 + 2 * e) * 72 + ll] = (u16)(u & 0xffffu);
;           BTs[(c8 * 8 + 2 * e + 1) * 72 + ll] = (u16)(u >> 16);
;         }
;       }
;       {
;         float w0 = cwX[0 * 32 + chg], w1 = cwX[1 * 32 + chg], w2 = cwX[2 * 32 + chg], w3 = cwX[3 * 32 + chg], bx = cwX[4 * 32 + chg];
;         float raw[7];
; #pragma unroll
;         for (int i = 0; i < 7; ++i) raw[i] = bf2f(rX[i]);
;         const float cs63 = cs[63];
;         float4 dt4 = *(const float4*)(dv + l0), cs4 = *(const float4*)(cs + l0);
;         float dts[4] = {dt4.x, dt4.y, dt4.z, dt4.w}, css[4] = {cs4.x, cs4.y, cs4.z, cs4.w};
;         float vx[4], vd[4], vw[4];
; #pragma unroll
;         for (int j = 0; j < 4; ++j) {
;           float s = bx + w0 * raw[j] + w1 * raw[j + 1] + w2 * raw[j + 2] + w3 * raw[j + 3];
;           vx[j] = siluf_(s);
;           vd[j] = vx[j] * dts[j];
;           vw[j] = vd[j] * __expf(cs63 - css[j]);
;         }
.LBB0_1033:
	s_bfe_i32 s3, s76, 0x10000
	s_and_b32 s3, s3, 0x15800
	v_lshl_or_b32 v32, v59, 1, s3
	s_lshl_b32 s31, s97, 8
	ds_write_b128 v116, v[20:23] offset:17408
	v_lshl_add_u32 v20, v146, 1, v32
	s_add_i32 s52, s31, 0x1e200
	ds_write_b128 v20, v[16:19]
	ds_write_b16 v52, v12 offset:34816
	ds_write_b16_d16_hi v52, v12 offset:34960
	ds_write_b16 v52, v13 offset:35104
	ds_write_b16_d16_hi v52, v13 offset:35248
	ds_write_b16 v52, v14 offset:35392
	ds_write_b16_d16_hi v52, v14 offset:35536
	ds_write_b16 v52, v15 offset:35680
	ds_write_b16_d16_hi v52, v15 offset:35824
	ds_write_b128 v117, v[24:27] offset:17408
	v_lshl_add_u32 v12, v147, 1, v32
	ds_write_b128 v12, v[28:31]
	ds_write_b16 v54, v8 offset:34816
	ds_write_b16_d16_hi v54, v8 offset:34960
	ds_write_b16 v54, v9 offset:35104
	ds_write_b16_d16_hi v54, v9 offset:35248
	ds_write_b16 v54, v10 offset:35392
	ds_write_b16_d16_hi v54, v10 offset:35536
	ds_write_b16 v54, v11 offset:35680
	ds_write_b16_d16_hi v54, v11 offset:35824
	v_mov_b32_e32 v8, s52
	ds_read2_b32 v[16:17], v115 offset1:32
	ds_read2_b32 v[18:19], v115 offset0:64 offset1:96
	ds_read_b32 v20, v115 offset:512
	ds_read_b32 v21, v8 offset:252
	v_and_b32_e32 v23, 0xffff0000, v173
	v_lshlrev_b32_e32 v22, 16, v173
	v_and_b32_e32 v13, 0xffff0000, v171
	v_lshlrev_b32_e32 v12, 16, v171
	v_add_u32_e32 v31, s31, v114
	v_lshlrev_b32_e32 v24, 16, v101
	s_waitcnt lgkmcnt(0)
	v_pk_fma_f32 v[14:15], v[16:17], v[12:13], v[20:21] op_sel_hi:[0,1,0]
	v_mov_b32_e32 v30, v17
	v_pk_mov_b32 v[12:13], v[12:13], v[22:23] op_sel:[1,0]
	v_lshlrev_b32_e32 v26, 16, v100
	v_pk_fma_f32 v[12:13], v[30:31], v[12:13], v[14:15] op_sel_hi:[0,1,1]
	v_mov_b32_e32 v14, v22
	v_mov_b32_e32 v15, v24
	v_pk_fma_f32 v[12:13], v[18:19], v[14:15], v[12:13] op_sel_hi:[0,1,1]
	v_mov_b32_e32 v32, v19
	v_mov_b32_e32 v14, v24
	v_mov_b32_e32 v15, v26
	v_pk_fma_f32 v[12:13], v[32:33], v[14:15], v[12:13] op_sel_hi:[0,1,1]
	v_and_b32_e32 v25, 0xffff0000, v101
	v_mul_f32_e32 v14, 0xbfb8aa3b, v12
	v_mul_f32_e32 v15, 0xbfb8aa3b, v13
	v_pk_fma_f32 v[16:17], v[16:17], v[22:23], v[20:21] op_sel_hi:[0,1,0]
	v_and_b32_e32 v27, 0xffff0000, v100
	v_exp_f32_e32 v14, v14
	v_exp_f32_e32 v15, v15
	v_pk_fma_f32 v[16:17], v[30:31], v[24:25], v[16:17] op_sel_hi:[0,1,1]
	v_and_b32_e32 v29, 0xffff0000, v42
	v_lshlrev_b32_e32 v28, 16, v42
	v_pk_fma_f32 v[16:17], v[18:19], v[26:27], v[16:17] op_sel_hi:[0,1,1]
	v_pk_fma_f32 v[16:17], v[32:33], v[28:29], v[16:17] op_sel_hi:[0,1,1]
	v_lshl_add_u32 v8, v50, 2, s52
	v_mul_f32_e32 v18, 0xbfb8aa3b, v16
	v_mul_f32_e32 v19, 0xbfb8aa3b, v17
	ds_read_b128 v[8:11], v8
	v_add_f32_e32 v14, 1.0, v14
	v_add_f32_e32 v15, 1.0, v15
	v_exp_f32_e32 v18, v18
	v_exp_f32_e32 v19, v19
	v_rcp_f32_e32 v14, v14
	v_rcp_f32_e32 v15, v15
	v_add_f32_e32 v18, 1.0, v18
	v_add_f32_e32 v19, 1.0, v19
	v_rcp_f32_e32 v18, v18
	v_pk_mul_f32 v[34:35], v[12:13], v[14:15]
	ds_read_b128 v[12:15], v31
	s_waitcnt lgkmcnt(1)
	v_sub_f32_e32 v8, v21, v8
	v_sub_f32_e32 v9, v21, v9
	v_sub_f32_e32 v10, v21, v10
	v_rcp_f32_e32 v19, v19
	v_sub_f32_e32 v11, v21, v11
	v_mul_f32_e32 v8, 0x3fb8aa3b, v8
	v_mul_f32_e32 v9, 0x3fb8aa3b, v9
	v_mul_f32_e32 v10, 0x3fb8aa3b, v10
	v_mul_f32_e32 v11, 0x3fb8aa3b, v11
	v_exp_f32_e32 v8, v8
	v_exp_f32_e32 v9, v9
	v_exp_f32_e32 v10, v10
	v_exp_f32_e32 v11, v11
	s_and_b32 s30, s76, 1
	s_cmp_eq_u32 s30, 0
	s_mov_b32 s30, 0xf400
	v_pk_mul_f32 v[16:17], v[16:17], v[18:19]
	s_cselect_b32 s77, s30, 0x1ae00
	s_waitcnt lgkmcnt(0)
; template <int DUMMY>
; __device__ void ssd_item(const Params& p, int item) {
;     ...
;       const u16* rp = bc + (tb + c * 64 + (idx >> 4)) * 2048 + grp * 128 + (idx & 15) * 8;
;       rBs[i] = *(const i32x4*)rp;
;       rCs[i] = *(const i32x4*)(rp + 1024);
;       rBT[i] = *(const i32x4*)(bc + (tb + c * 64 + (idx & 63)) * 2048 + grp * 128 + (idx >> 6) * 8);
;     }
; #pragma unroll
;     for (int i = 0; i < 7; ++i) {
;       int row = c * 64 + l0 - 3 + i;
;       rX[i] = row >= 0 ? xbc[(tb + row) * 6144 + colX + chg] : (u16)0;
;     }
;     ...
;         *(i32x2*)(xT + chg * 72 + l0) = i32x2{(int)pack2(vx[0], vx[1]), (int)pack2(vx[2], vx[3])};
;         *(i32x2*)(xdT + chg * 72 + l0) = i32x2{(int)pack2(vd[0], vd[1]), (int)pack2(vd[2], vd[3])};
;         *(i32x2*)(xwT + chg * 72 + l0) = i32x2{(int)pack2(vw[0], vw[1]), (int)pack2(vw[2], vw[3])};
;       }
;     }
; #pragma unroll
;     for (int j = 0; j < 2; ++j)
; #pragma unroll
;       for (int r = 0; r < 4; ++r) Sb[(pf * 16 + g4 * 4 + r) * 136 + (nf0 + j) * 16 + fr] = f2bf(accS[j][r]);
; #pragma unroll
;     for (int r = 0; r < 4; ++r) zcur[r] = znext[r];
;     if (c > 1) {
;       const size_t yi = (tb + (c - 2) * 64 + (tid >> 3)) * 4096 + h * 64 + ph * 32 + (tid & 7) * 4;
;       *(i32x2*)(zyo + (yi & omask)) = ypend;
;     }
;     if (c + 1 < 128) {
;       load_raw(c + 1);
;       const size_t zn = zbase + (size_t)64 * 4096;
; #pragma unroll
;       for (int r = 0; r < 4; ++r) znext[r] = zy[zn + (size_t)r * 4096];
;       if (wid == 0) {
;         float dt_use = dt_n;
;         if (c + 2 < 128) dt_n = dtb[(tb + (c + 2) * 64 + lane) * 64 + h];
;         write_cs(dt_use, nxt3);
;       }
	v_pk_mul_f32 v[12:13], v[12:13], v[34:35]
	v_pk_mul_f32 v[14:15], v[14:15], v[16:17]
	s_mov_b32 s30, 0xd000
	v_pk_mul_f32 v[8:9], v[8:9], v[12:13]
	v_pk_mul_f32 v[10:11], v[14:15], v[10:11]
	s_cselect_b32 s53, s30, 0x19c00
	v_cvt_pk_bf16_f32 v19, v16, v17
	v_lshlrev_b32_e32 v16, 1, v143
	s_cselect_b32 s78, 0x12a00, s93
	v_cvt_pk_bf16_f32 v18, v34, v35
	v_add3_u32 v17, s77, v16, v144
	v_cvt_pk_bf16_f32 v12, v12, v13
	v_cvt_pk_bf16_f32 v13, v14, v15
	v_add3_u32 v14, s53, v16, v144
	v_cvt_pk_bf16_f32 v8, v8, v9
	v_cvt_pk_bf16_f32 v9, v10, v11
	ds_write_b64 v17, v[18:19]
	ds_write_b64 v14, v[12:13]
	ds_write_b64 v113, v[8:9] offset:57856
	v_lshl_or_b32 v8, v56, 1, s78
	v_cvt_pk_bf16_f32 v9, v4, s0
	v_add3_u32 v10, v8, v55, v159
	ds_write_b16 v10, v9
	v_cvt_pk_bf16_f32 v9, v5, s0
	ds_write_b16 v10, v9 offset:272
	v_cvt_pk_bf16_f32 v9, v6, s0
	ds_write_b16 v10, v9 offset:544
	v_cvt_pk_bf16_f32 v9, v7, s0
	ds_write_b16 v10, v9 offset:816
	v_cvt_pk_bf16_f32 v9, v0, s0
	v_add3_u32 v8, v8, v153, v159
	ds_write_b16 v8, v9
	v_cvt_pk_bf16_f32 v9, v1, s0
	ds_write_b16 v8, v9 offset:272
	v_cvt_pk_bf16_f32 v9, v2, s0
	ds_write_b16 v8, v9 offset:544
	v_cvt_pk_bf16_f32 v9, v3, s0
	ds_write_b16 v8, v9 offset:816
	v_lshl_add_u64 v[8:9], s[42:43], 0, v[98:99]
	global_store_dwordx2 v[8:9], v[82:83], off
	v_lshl_add_u64 v[8:9], v[78:79], 0, s[70:71]
	s_mov_b32 s30, 0xc0000
	v_add_co_u32_e32 v8, vcc, s30, v8
	v_add_u32_e32 v40, -6, v86
	s_nop 0
	v_addc_co_u32_e32 v9, vcc, 0, v9, vcc
	global_load_dwordx4 v[20:23], v[8:9], off
	global_load_dwordx4 v[16:19], v[8:9], off offset:2048
	v_lshl_add_u64 v[8:9], v[90:91], 0, s[70:71]
	global_load_dwordx4 v[12:15], v[8:9], off
	v_lshl_add_u64 v[8:9], v[80:81], 0, s[70:71]
	v_add_co_u32_e32 v8, vcc, 0xc0000, v8
	v_mov_b32_e32 v172, 0
	s_nop 0
	v_addc_co_u32_e32 v9, vcc, 0, v9, vcc
	global_load_dwordx4 v[24:27], v[8:9], off
	global_load_dwordx4 v[28:31], v[8:9], off offset:2048
	v_lshl_add_u64 v[8:9], v[88:89], 0, s[70:71]
	global_load_dwordx4 v[8:11], v[8:9], off
	v_lshl_add_u64 v[32:33], s[64:65], 0, v[40:41]
	v_mad_u64_u32 v[34:35], s[72:73], v32, s86, v[66:67]
	v_mad_i32_i24 v35, v33, s86, v35
	global_load_ushort v171, v[34:35], off
	v_add_co_u32_e32 v34, vcc, 0x3000, v34
	s_nop 1
	v_addc_co_u32_e32 v35, vcc, 0, v35, vcc
	global_load_ushort v172, v[34:35], off
	v_add_co_u32_e32 v34, vcc, 0x3000, v34
	s_nop 1
	v_addc_co_u32_e32 v35, vcc, 0, v35, vcc
	global_load_ushort v174, v[34:35], off
	v_add_co_u32_e32 v34, vcc, 0x3000, v34
	s_nop 1
	v_addc_co_u32_e32 v35, vcc, 0, v35, vcc
	global_load_ushort v173, v[34:35], off
	v_add_co_u32_e32 v34, vcc, 0x3000, v34
	s_nop 1
	v_addc_co_u32_e32 v35, vcc, 0, v35, vcc
	global_load_ushort v175, v[34:35], off
	v_add_co_u32_e32 v34, vcc, 0x3000, v34
	s_nop 1
	v_addc_co_u32_e32 v35, vcc, 0, v35, vcc
	global_load_ushort v176, v[34:35], off
	v_add_co_u32_e32 v34, vcc, 0x3000, v34
	s_nop 1
	v_addc_co_u32_e32 v35, vcc, 0, v35, vcc
	global_load_ushort v40, v[34:35], off
	v_lshl_add_u64 v[32:33], s[42:43], 0, v[84:85]
	v_add_co_u32_e32 v34, vcc, 0xb280000, v32
	s_add_i32 s30, s97, 1
	s_nop 0
	v_addc_co_u32_e32 v35, vcc, 0, v33, vcc
	global_load_ushort v170, v[34:35], off
	v_add_co_u32_e32 v34, vcc, 0xb282000, v32
	s_cmp_lg_u32 s97, 2
	s_nop 0
	v_addc_co_u32_e32 v35, vcc, 0, v33, vcc
	global_load_ushort v169, v[34:35], off
	v_add_co_u32_e32 v34, vcc, 0xb284000, v32
	s_cselect_b32 s97, s30, 0
	s_nop 0
	v_addc_co_u32_e32 v35, vcc, 0, v33, vcc
	v_add_co_u32_e32 v32, vcc, 0xb286000, v32
	global_load_ushort v168, v[34:35], off
	s_nop 0
	v_addc_co_u32_e32 v33, vcc, 0, v33, vcc
	global_load_ushort v49, v[32:33], off
	s_and_saveexec_b64 s[30:31], s[4:5]
	s_cbranch_execz .LBB0_1049
	v_lshl_add_u64 v[32:33], s[42:43], 0, v[92:93]
	global_load_dword v255, v[32:33], off
	v_mul_f32_e64 v33, v118, -v120
	s_nop 1
	v_mov_b32_dpp v33, v33 row_shr:1 row_mask:0xf bank_mask:0xf bound_ctrl:1
	v_fma_f32 v33, v118, -v120, v33
	s_nop 1
	v_add_f32_dpp v33, v33, v33 row_shr:2 row_mask:0xf bank_mask:0xf bound_ctrl:1
	s_nop 1
	v_add_f32_dpp v33, v33, v33 row_shr:4 row_mask:0xf bank_mask:0xf bound_ctrl:1
	s_nop 1
	v_add_f32_dpp v33, v33, v33 row_shr:8 row_mask:0xf bank_mask:0xf bound_ctrl:1
	s_nop 0
	v_readlane_b32 s72, v33, 15
	v_readlane_b32 s73, v33, 31
	v_readlane_b32 vcc_lo, v33, 47
	v_mov_b32_e32 v34, s72
	v_mov_b32_e32 v35, s73
	v_cndmask_b32_e64 v34, v34, 0, s[26:27]
	v_cndmask_b32_e64 v35, 0, v35, s[24:25]
	v_add_f32_e32 v34, v34, v35
	v_mov_b32_e32 v35, vcc_lo
	v_cndmask_b32_e64 v35, 0, v35, s[22:23]
	v_add_f32_e32 v34, v35, v34
	v_add_f32_e32 v33, v33, v34
	v_lshl_or_b32 v34, s97, 8, v135
	v_add_u32_e32 v35, 0x1e200, v34
	ds_write_b32 v35, v33
	v_add_u32_e32 v33, 0x1e500, v34
	ds_write_b32 v33, v118
